# phase-0 cache conversion loops: two float4 per thread per iteration (2 loads in flight, 16B stores), on top of small-loop load hoisting
# baseline (speedup 1.0000x reference)
; __device__ __forceinline__ unsigned pk2(float lo, float hi) { f32x2 v = {lo, hi}; bf16x2_t b = __builtin_convertvector(v, bf16x2_t); return __builtin_bit_cast(unsigned, b); }
; __device__ __forceinline__ void conv_rows(const float* src, bf16_t* dst, int B, int R, int C, int dstB, int dstOff, int gtid, int gthreads) {
;     const int c4 = C / 4; const long total = (long)B * R * c4;
;     for (long i = gtid; i < total; i += gthreads) { const int cc = (int)(i % c4); const long br = i / c4; const int rr = (int)(br % R), b = (int)(br / R);
;         const f32x4 v = *(const f32x4*)(src + ((size_t)br * C + cc * 4)); u32x2 o; o.x = pk2(v[0], v[1]); o.y = pk2(v[2], v[3]);
;         __builtin_nontemporal_store(o, (u32x2*)(dst + ((size_t)(b * dstB + dstOff + rr) * C + cc * 4))); }
; }
; __global__ void __launch_bounds__(512, 2) fwd_kernel(Params P) {
;     ...
;         conv_rows(P.in[2], KAS, 8, 1024, 512, LKSP, 0, gtid, gthreads);
;         conv_rows(P.in[3], VAS, 8, 1024, 512, LKSP, 0, gtid, gthreads);
;         conv_rows(P.in[4], LAT + (size_t)NP * 256, 8, 1024, 256, LKSP, 0, gtid, gthreads);
.LBB0_92:
	s_load_dwordx16 s[36:51], s[0:1], 0x0
	s_lshl_b32 s66, s94, 9
	s_add_u32 s84, s92, 0x1bf90000
	s_addc_u32 s85, s93, 0
	v_lshl_add_u32 v176, s2, 9, v178
	s_add_u32 s88, s92, 0x1c810000
	s_mov_b32 s0, 0x100000
	s_addc_u32 s89, s93, 0
	v_ashrrev_i32_e32 v177, 31, v176
	v_cmp_gt_i32_e32 vcc, s0, v176
	v_lshlrev_b32_e32 v239, 2, v178
	s_and_saveexec_b64 s[4:5], vcc
	s_cbranch_execz .LBB0_97
	v_lshl_add_u32 v1, s2, 11, v239
	s_ashr_i32 s67, s66, 31
	s_lshl_b32 s12, s94, 11
	s_mov_b64 s[6:7], 0
	v_mov_b32_e32 v3, 0
	s_movk_i32 s13, 0x440
	s_mov_b64 s[8:9], 0xfffff
	v_mov_b32_e32 v6, v1
	v_mov_b64_e32 v[4:5], v[176:177]
	v_lshlrev_b32_e32 v6, 1, v6
	v_lshlrev_b64 v[4:5], 1, v[4:5]
	s_lshl_b64 s[100:101], s[66:67], 1
	s_lshl_b32 s99, s12, 1
.LBB0_94:
	v_ashrrev_i32_e32 v7, 31, v5
	v_lshrrev_b32_e32 v2, 25, v7
	v_lshl_add_u64 v[12:13], v[4:5], 0, v[2:3]
	v_ashrrev_i64 v[14:15], 7, v[12:13]
	v_lshlrev_b32_e32 v2, 9, v14
	v_lshlrev_b64 v[8:9], 11, v[14:15]
	v_sub_u32_e32 v16, v6, v2
	s_waitcnt lgkmcnt(0)
	v_lshl_add_u64 v[8:9], s[40:41], 0, v[8:9]
	v_ashrrev_i32_e32 v17, 31, v16
	v_lshl_add_u64 v[8:9], v[16:17], 2, v[8:9]
	global_load_dwordx4 v[248:251], v[8:9], off offset:16
	global_load_dwordx4 v[8:11], v[8:9], off
	v_lshrrev_b32_e32 v2, 15, v7
	v_ashrrev_i32_e32 v7, 31, v13
	v_lshl_add_u64 v[18:19], v[4:5], 0, v[2:3]
	v_lshrrev_b32_e32 v2, 22, v7
	v_add_u32_e32 v2, v14, v2
	v_lshl_add_u64 v[4:5], v[4:5], 0, s[100:101]
	v_and_b32_e32 v2, 0xfffffc00, v2
	v_alignbit_b32 v7, v19, v18, 17
	v_cmp_lt_i64_e64 s[0:1], s[8:9], v[4:5]
	v_sub_u32_e32 v2, v14, v2
	s_or_b64 s[6:7], s[0:1], s[6:7]
	v_mad_u64_u32 v[14:15], s[0:1], v7, s13, v[2:3]
	v_mov_b32_e32 v12, v3
	v_mov_b32_e32 v13, v14
	v_ashrrev_i64 v[12:13], 22, v[12:13]
	v_lshl_add_u64 v[12:13], s[84:85], 0, v[12:13]
	v_add_u32_e32 v6, s99, v6
	v_lshl_add_u64 v[12:13], v[16:17], 1, v[12:13]
	s_waitcnt vmcnt(0)
	v_cvt_pk_bf16_f32 v8, v8, v9
	v_cvt_pk_bf16_f32 v9, v10, v11
	v_cvt_pk_bf16_f32 v10, v248, v249
	v_cvt_pk_bf16_f32 v11, v250, v251
	global_store_dwordx4 v[12:13], v[8:11], off nt
	s_andn2_b64 exec, exec, s[6:7]
	s_cbranch_execnz .LBB0_94
	s_or_b64 exec, exec, s[6:7]
	s_mov_b64 s[6:7], 0
	v_mov_b32_e32 v3, 0
	s_movk_i32 s13, 0x440
	s_mov_b64 s[8:9], 0xfffff
	v_mov_b64_e32 v[4:5], v[176:177]
	v_lshlrev_b32_e32 v1, 1, v1
	v_lshlrev_b64 v[4:5], 1, v[4:5]
	s_lshl_b64 s[100:101], s[66:67], 1
	s_lshl_b32 s99, s12, 1
.LBB0_96:
	v_ashrrev_i32_e32 v16, 31, v5
	v_lshrrev_b32_e32 v2, 25, v16
	v_lshl_add_u64 v[10:11], v[4:5], 0, v[2:3]
	v_ashrrev_i64 v[12:13], 7, v[10:11]
	v_lshlrev_b32_e32 v2, 9, v12
	v_lshlrev_b64 v[6:7], 11, v[12:13]
	v_sub_u32_e32 v14, v1, v2
	v_lshl_add_u64 v[6:7], s[42:43], 0, v[6:7]
	v_ashrrev_i32_e32 v15, 31, v14
	v_lshl_add_u64 v[6:7], v[14:15], 2, v[6:7]
	global_load_dwordx4 v[248:251], v[6:7], off offset:16
	global_load_dwordx4 v[6:9], v[6:7], off
	v_lshrrev_b32_e32 v2, 15, v16
	v_ashrrev_i32_e32 v11, 31, v11
	v_lshl_add_u64 v[16:17], v[4:5], 0, v[2:3]
	v_lshrrev_b32_e32 v2, 22, v11
	v_add_u32_e32 v2, v12, v2
	v_lshl_add_u64 v[4:5], v[4:5], 0, s[100:101]
	v_and_b32_e32 v2, 0xfffffc00, v2
	v_alignbit_b32 v11, v17, v16, 17
	v_cmp_lt_i64_e64 s[0:1], s[8:9], v[4:5]
	v_sub_u32_e32 v2, v12, v2
	s_or_b64 s[6:7], s[0:1], s[6:7]
	v_mad_u64_u32 v[12:13], s[0:1], v11, s13, v[2:3]
	v_mov_b32_e32 v10, v3
	v_mov_b32_e32 v11, v12
	v_ashrrev_i64 v[10:11], 22, v[10:11]
	v_lshl_add_u64 v[10:11], s[88:89], 0, v[10:11]
	v_add_u32_e32 v1, s99, v1
	v_lshl_add_u64 v[10:11], v[14:15], 1, v[10:11]
	s_waitcnt vmcnt(0)
	v_cvt_pk_bf16_f32 v6, v6, v7
	v_cvt_pk_bf16_f32 v7, v8, v9
	v_cvt_pk_bf16_f32 v8, v248, v249
	v_cvt_pk_bf16_f32 v9, v250, v251
	global_store_dwordx4 v[10:11], v[6:9], off nt
	s_andn2_b64 exec, exec, s[6:7]
	s_cbranch_execnz .LBB0_96
.LBB0_97:
	s_waitcnt lgkmcnt(0)
	v_writelane_b32 v254, s36, 38
	s_nop 1
	v_writelane_b32 v254, s37, 39
	v_writelane_b32 v254, s38, 40
	v_writelane_b32 v254, s39, 41
	v_writelane_b32 v254, s40, 42
	v_writelane_b32 v254, s41, 43
	v_writelane_b32 v254, s42, 44
	v_writelane_b32 v254, s43, 45
	v_writelane_b32 v254, s44, 46
	v_writelane_b32 v254, s45, 47
	v_writelane_b32 v254, s46, 48
	v_writelane_b32 v254, s47, 49
	v_writelane_b32 v254, s48, 50
	v_writelane_b32 v254, s49, 51
	v_writelane_b32 v254, s50, 52
	v_writelane_b32 v254, s51, 53
	s_or_b64 exec, exec, s[4:5]
	s_add_u32 s8, s92, 0x1b640000
	s_mov_b32 s0, 0x80000
	s_addc_u32 s9, s93, 0
	v_cmp_gt_i32_e64 s[0:1], s0, v176
	s_and_saveexec_b64 s[4:5], s[0:1]
	v_readlane_b32 s36, v254, 38
	v_readlane_b32 s44, v254, 46
	v_readlane_b32 s45, v254, 47
	v_readlane_b32 s37, v254, 39
	v_readlane_b32 s38, v254, 40
	v_readlane_b32 s39, v254, 41
	v_readlane_b32 s40, v254, 42
	v_readlane_b32 s41, v254, 43
	v_readlane_b32 s42, v254, 44
	v_readlane_b32 s43, v254, 45
	v_readlane_b32 s46, v254, 48
	v_readlane_b32 s47, v254, 49
	v_readlane_b32 s48, v254, 50
	v_readlane_b32 s49, v254, 51
	v_readlane_b32 s50, v254, 52
	v_readlane_b32 s51, v254, 53
	s_cbranch_execz .LBB0_100
	s_ashr_i32 s67, s66, 31
	v_lshl_add_u32 v1, s2, 11, v239
	s_lshl_b32 s16, s94, 11
	s_mov_b64 s[6:7], 0
	v_mov_b32_e32 v3, 0
	s_movk_i32 s17, 0x440
	s_mov_b64 s[12:13], 0x7ffff
	v_mov_b64_e32 v[4:5], v[176:177]
	v_lshlrev_b32_e32 v1, 1, v1
	v_lshlrev_b64 v[4:5], 1, v[4:5]
	s_lshl_b64 s[100:101], s[66:67], 1
	s_lshl_b32 s99, s16, 1
.LBB0_99:
	v_ashrrev_i32_e32 v16, 31, v5
	v_lshrrev_b32_e32 v2, 26, v16
	v_lshl_add_u64 v[10:11], v[4:5], 0, v[2:3]
	v_ashrrev_i64 v[12:13], 6, v[10:11]
	v_lshlrev_b32_e32 v2, 8, v12
	v_lshlrev_b64 v[6:7], 10, v[12:13]
	v_sub_u32_e32 v14, v1, v2
	v_lshl_add_u64 v[6:7], s[44:45], 0, v[6:7]
	v_ashrrev_i32_e32 v15, 31, v14
	v_lshl_add_u64 v[6:7], v[14:15], 2, v[6:7]
	global_load_dwordx4 v[248:251], v[6:7], off offset:16
	global_load_dwordx4 v[6:9], v[6:7], off
	v_lshrrev_b32_e32 v2, 16, v16
	v_ashrrev_i32_e32 v11, 31, v11
	v_lshl_add_u64 v[16:17], v[4:5], 0, v[2:3]
	v_lshrrev_b32_e32 v2, 22, v11
	v_add_u32_e32 v2, v12, v2
	v_lshl_add_u64 v[4:5], v[4:5], 0, s[100:101]
	v_and_b32_e32 v2, 0xfffffc00, v2
	v_alignbit_b32 v11, v17, v16, 16
	v_cmp_lt_i64_e64 s[0:1], s[12:13], v[4:5]
	v_sub_u32_e32 v2, v12, v2
	s_or_b64 s[6:7], s[0:1], s[6:7]
	v_mad_u64_u32 v[12:13], s[0:1], v11, s17, v[2:3]
	v_mov_b32_e32 v10, v3
	v_mov_b32_e32 v11, v12
	v_ashrrev_i64 v[10:11], 23, v[10:11]
	v_lshl_add_u64 v[10:11], s[8:9], 0, v[10:11]
	v_add_u32_e32 v1, s99, v1
	v_lshl_add_u64 v[10:11], v[14:15], 1, v[10:11]
	s_waitcnt vmcnt(0)
	v_cvt_pk_bf16_f32 v6, v6, v7
	v_cvt_pk_bf16_f32 v7, v8, v9
	v_cvt_pk_bf16_f32 v8, v248, v249
	v_cvt_pk_bf16_f32 v9, v250, v251
	global_store_dwordx4 v[10:11], v[6:9], off nt
	s_andn2_b64 exec, exec, s[6:7]
	s_cbranch_execnz .LBB0_99

; __device__ __forceinline__ unsigned pk2(float lo, float hi) { f32x2 v = {lo, hi}; bf16x2_t b = __builtin_convertvector(v, bf16x2_t); return __builtin_bit_cast(unsigned, b); }
; __device__ __forceinline__ void conv_rows(const float* src, bf16_t* dst, int B, int R, int C, int dstB, int dstOff, int gtid, int gthreads) {
;     const int c4 = C / 4; const long total = (long)B * R * c4;
;     for (long i = gtid; i < total; i += gthreads) { const int cc = (int)(i % c4); const long br = i / c4; const int rr = (int)(br % R), b = (int)(br / R);
;         const f32x4 v = *(const f32x4*)(src + ((size_t)br * C + cc * 4)); u32x2 o; o.x = pk2(v[0], v[1]); o.y = pk2(v[2], v[3]);
;         __builtin_nontemporal_store(o, (u32x2*)(dst + ((size_t)(b * dstB + dstOff + rr) * C + cc * 4))); }
; }
; __global__ void __launch_bounds__(512, 2) fwd_kernel(Params P) {
;     ...
;         conv_rows(P.in[6], KCS, 8, 512, 1024, LCSP, 0, gtid, gthreads);
;         conv_rows(P.in[7], VCS, 8, 512, 1024, LCSP, 0, gtid, gthreads);
.LBB0_103:
	s_or_b64 exec, exec, s[6:7]
	s_add_u32 s80, s92, 0x1d090000
	s_addc_u32 s81, s93, 0
	s_add_u32 s74, s92, 0x1d990000
	s_addc_u32 s75, s93, 0
	s_and_saveexec_b64 s[0:1], vcc
	v_readlane_b32 s36, v254, 38
	v_readlane_b32 s48, v254, 50
	v_readlane_b32 s49, v254, 51
	v_readlane_b32 s50, v254, 52
	v_readlane_b32 s51, v254, 53
	v_readlane_b32 s37, v254, 39
	v_readlane_b32 s38, v254, 40
	v_readlane_b32 s39, v254, 41
	v_readlane_b32 s40, v254, 42
	v_readlane_b32 s41, v254, 43
	v_readlane_b32 s42, v254, 44
	v_readlane_b32 s43, v254, 45
	v_readlane_b32 s44, v254, 46
	v_readlane_b32 s45, v254, 47
	v_readlane_b32 s46, v254, 48
	v_readlane_b32 s47, v254, 49
	s_cbranch_execz .LBB0_108
	s_mov_b64 s[28:29], s[48:49]
	v_lshl_add_u32 v1, s2, 11, v239
	s_mov_b64 s[30:31], s[50:51]
	s_ashr_i32 s67, s66, 31
	s_lshl_b32 s16, s94, 11
	s_mov_b64 s[6:7], 0
	v_mov_b32_e32 v3, 0
	s_movk_i32 s17, 0x240
	s_mov_b64 s[12:13], 0xfffff
	v_mov_b32_e32 v6, v1
	v_mov_b64_e32 v[4:5], v[176:177]
	v_lshlrev_b32_e32 v6, 1, v6
	v_lshlrev_b64 v[4:5], 1, v[4:5]
	s_lshl_b64 s[100:101], s[66:67], 1
	s_lshl_b32 s99, s16, 1
.LBB0_105:
	v_ashrrev_i32_e32 v7, 31, v5
	v_lshrrev_b32_e32 v2, 24, v7
	v_lshl_add_u64 v[12:13], v[4:5], 0, v[2:3]
	v_ashrrev_i64 v[14:15], 8, v[12:13]
	v_lshlrev_b32_e32 v2, 10, v14
	v_lshlrev_b64 v[8:9], 12, v[14:15]
	v_sub_u32_e32 v16, v6, v2
	v_lshl_add_u64 v[8:9], s[28:29], 0, v[8:9]
	v_ashrrev_i32_e32 v17, 31, v16
	v_lshl_add_u64 v[8:9], v[16:17], 2, v[8:9]
	global_load_dwordx4 v[248:251], v[8:9], off offset:16
	global_load_dwordx4 v[8:11], v[8:9], off
	v_lshrrev_b32_e32 v2, 15, v7
	v_ashrrev_i32_e32 v7, 31, v13
	v_lshl_add_u64 v[18:19], v[4:5], 0, v[2:3]
	v_lshrrev_b32_e32 v2, 23, v7
	v_add_u32_e32 v2, v14, v2
	v_and_b32_e32 v2, 0xfffffe00, v2
	v_alignbit_b32 v7, v19, v18, 17
	v_sub_u32_e32 v2, v14, v2
	v_mad_u64_u32 v[14:15], s[18:19], v7, s17, v[2:3]
	v_mov_b32_e32 v12, v3
	v_mov_b32_e32 v13, v14
	v_lshl_add_u64 v[4:5], v[4:5], 0, s[100:101]
	v_ashrrev_i64 v[12:13], 21, v[12:13]
	v_cmp_lt_i64_e32 vcc, s[12:13], v[4:5]
	v_lshl_add_u64 v[12:13], s[80:81], 0, v[12:13]
	v_add_u32_e32 v6, s99, v6
	s_or_b64 s[6:7], vcc, s[6:7]
	v_lshl_add_u64 v[12:13], v[16:17], 1, v[12:13]
	s_waitcnt vmcnt(0)
	v_cvt_pk_bf16_f32 v8, v8, v9
	v_cvt_pk_bf16_f32 v9, v10, v11
	v_cvt_pk_bf16_f32 v10, v248, v249
	v_cvt_pk_bf16_f32 v11, v250, v251
	global_store_dwordx4 v[12:13], v[8:11], off nt
	s_andn2_b64 exec, exec, s[6:7]
	s_cbranch_execnz .LBB0_105
	s_or_b64 exec, exec, s[6:7]
	s_mov_b64 s[6:7], 0
	v_mov_b32_e32 v3, 0
	s_movk_i32 s17, 0x240
	s_mov_b64 s[12:13], 0xfffff
	v_mov_b64_e32 v[4:5], v[176:177]
	v_lshlrev_b32_e32 v1, 1, v1
	v_lshlrev_b64 v[4:5], 1, v[4:5]
	s_lshl_b64 s[100:101], s[66:67], 1
	s_lshl_b32 s99, s16, 1
.LBB0_107:
	v_ashrrev_i32_e32 v16, 31, v5
	v_lshrrev_b32_e32 v2, 24, v16
	v_lshl_add_u64 v[10:11], v[4:5], 0, v[2:3]
	v_ashrrev_i64 v[12:13], 8, v[10:11]
	v_lshlrev_b32_e32 v2, 10, v12
	v_lshlrev_b64 v[6:7], 12, v[12:13]
	v_sub_u32_e32 v14, v1, v2
	v_lshl_add_u64 v[6:7], s[30:31], 0, v[6:7]
	v_ashrrev_i32_e32 v15, 31, v14
	v_lshl_add_u64 v[6:7], v[14:15], 2, v[6:7]
	global_load_dwordx4 v[248:251], v[6:7], off offset:16
	global_load_dwordx4 v[6:9], v[6:7], off
	v_lshrrev_b32_e32 v2, 15, v16
	v_ashrrev_i32_e32 v11, 31, v11
	v_lshl_add_u64 v[16:17], v[4:5], 0, v[2:3]
	v_lshrrev_b32_e32 v2, 23, v11
	v_add_u32_e32 v2, v12, v2
	v_and_b32_e32 v2, 0xfffffe00, v2
	v_alignbit_b32 v11, v17, v16, 17
	v_sub_u32_e32 v2, v12, v2
	v_mad_u64_u32 v[12:13], s[18:19], v11, s17, v[2:3]
	v_mov_b32_e32 v10, v3
	v_mov_b32_e32 v11, v12
	v_lshl_add_u64 v[4:5], v[4:5], 0, s[100:101]
	v_ashrrev_i64 v[10:11], 21, v[10:11]
	v_cmp_lt_i64_e32 vcc, s[12:13], v[4:5]
	v_lshl_add_u64 v[10:11], s[74:75], 0, v[10:11]
	v_add_u32_e32 v1, s99, v1
	s_or_b64 s[6:7], vcc, s[6:7]
	v_lshl_add_u64 v[10:11], v[14:15], 1, v[10:11]
	s_waitcnt vmcnt(0)
	v_cvt_pk_bf16_f32 v6, v6, v7
	v_cvt_pk_bf16_f32 v7, v8, v9
	v_cvt_pk_bf16_f32 v8, v248, v249
	v_cvt_pk_bf16_f32 v9, v250, v251
	global_store_dwordx4 v[10:11], v[6:9], off nt
	s_andn2_b64 exec, exec, s[6:7]
	s_cbranch_execnz .LBB0_107
